# q/kv projection items in feature-tile-fastest order (the tiles sharing a block of z rows run concurrently)
# speedup vs baseline: 1.0065x; 1.0006x over previous
; DEV float bflo(unsigned w) { return __uint_as_float(w << 16); }
; DEV float bfhi(unsigned w) { return __uint_as_float(w & 0xffff0000u); }
; #define OPQ int tid = tid0; asm volatile("" : "+v"(tid));
; DEV void row_scales(const u16* __restrict__ zrow0, int col0, int ncol, float* rs, int tid) {
;   if (tid >= 384) return;
;   const int r = tid >> 1, h = tid & 1, lane = tid & 63;
;   const u16* s = zrow0 + (long)r * NINP + col0 + h * (ncol / 2);
;   float ss = 0.f;
;   for (int i = 0; i < ncol / 2; i += 8) {
;     uint4 v = *(const uint4*)(s + i);
;     ss += bflo(v.x) * bflo(v.x) + bfhi(v.x) * bfhi(v.x) + bflo(v.y) * bflo(v.y) + bfhi(v.y) * bfhi(v.y) +
;           bflo(v.z) * bflo(v.z) + bfhi(v.z) * bfhi(v.z) + bflo(v.w) * bflo(v.w) + bfhi(v.w) * bfhi(v.w);
;   }
;   ss += shx(ss, 1, lane);
;   if (h == 0) rs[r] = rsqrtf(ss / (float)ncol + 1e-6f);
; }
; __global__ void __launch_bounds__(512) mega(Params p, int coop) {
;     ...
;         for (int j = xr; j < 72 + 96 + 9; j += xper) {
;           OPQ
;           if (j < 72) { if (!(last && (j % 12) == 0)) qproj_item(p, l, xx * 12 + j % 12, j / 12, smem, tid); }
;           else if (j < 168) kvproj_item(p, l, xx * 12 + (j - 72) % 12, (j - 72) / 12, smem, tid);
;           else krope_item(p, xx * 9 + (j - 168), tid);
.LBB0_755:
	s_and_b64 vcc, exec, s[6:7]
	s_cbranch_vccz .LBB0_765
	s_add_i32 s6, s15, 0xffb8
	s_and_b32 s7, s6, 0xff
	s_and_b32 s11, s7, 7
	s_lshr_b32 s6, s7, 3
	v_readlane_b32 s7, v255, 10
	s_add_i32 s10, s7, s6
	s_mul_i32 s6, s10, 0x330000
	s_add_u32 s6, s88, s6
	s_movk_i32 s8, 0x180
	s_addc_u32 s7, s89, 0
	v_cmp_gt_i32_e32 vcc, s8, v58
	s_barrier
	s_and_saveexec_b64 s[8:9], vcc
	s_cbranch_execz .LBB0_759
	v_ashrrev_i32_e32 v16, 1, v58
	v_and_b32_e32 v17, 1, v58
	v_mov_b64_e32 v[0:1], s[6:7]
	v_mad_i64_i32 v[0:1], s[16:17], v16, s33, v[0:1]
	v_lshlrev_b32_e32 v156, 7, v17
	s_waitcnt lgkmcnt(0)
	v_lshl_add_u64 v[12:13], v[0:1], 0, v[156:157]
	global_load_dwordx4 v[0:3], v[12:13], off offset:560
	global_load_dwordx4 v[4:7], v[12:13], off offset:544
	global_load_dwordx4 v[8:11], v[12:13], off offset:528
	global_load_dwordx4 v[18:21], v[12:13], off offset:512
	global_load_dwordx4 v[100:103], v[12:13], off offset:624
	global_load_dwordx4 v[104:107], v[12:13], off offset:608
	global_load_dwordx4 v[108:111], v[12:13], off offset:592
	global_load_dwordx4 v[112:115], v[12:13], off offset:576
	v_cmp_eq_u32_e32 vcc, 0, v17
	s_waitcnt vmcnt(4)
	v_and_b32_e32 v15, 0xffff0000, v18
	v_lshlrev_b32_e32 v14, 16, v18
	v_mul_f32_e32 v15, v15, v15
	v_fmac_f32_e32 v15, v14, v14
	v_lshlrev_b32_e32 v14, 16, v19
	v_fmac_f32_e32 v15, v14, v14
	v_and_b32_e32 v14, 0xffff0000, v19
	v_fmac_f32_e32 v15, v14, v14
	v_lshlrev_b32_e32 v14, 16, v20
	v_fmac_f32_e32 v15, v14, v14
	v_and_b32_e32 v14, 0xffff0000, v20
	v_fmac_f32_e32 v15, v14, v14
	v_lshlrev_b32_e32 v14, 16, v21
	v_fmac_f32_e32 v15, v14, v14
	v_and_b32_e32 v14, 0xffff0000, v21
	v_fmac_f32_e32 v15, v14, v14
	v_lshlrev_b32_e32 v14, 16, v8
	v_and_b32_e32 v8, 0xffff0000, v8
	v_mul_f32_e32 v8, v8, v8
	v_fmac_f32_e32 v8, v14, v14
	v_lshlrev_b32_e32 v14, 16, v9
	v_fmac_f32_e32 v8, v14, v14
	v_and_b32_e32 v9, 0xffff0000, v9
	v_fmac_f32_e32 v8, v9, v9
	v_lshlrev_b32_e32 v9, 16, v10
	v_fmac_f32_e32 v8, v9, v9
	v_and_b32_e32 v9, 0xffff0000, v10
	v_fmac_f32_e32 v8, v9, v9
	v_lshlrev_b32_e32 v9, 16, v11
	v_fmac_f32_e32 v8, v9, v9
	v_and_b32_e32 v9, 0xffff0000, v11
	v_fmac_f32_e32 v8, v9, v9
	v_lshlrev_b32_e32 v9, 16, v4
	v_and_b32_e32 v4, 0xffff0000, v4
	v_mul_f32_e32 v4, v4, v4
	v_fmac_f32_e32 v4, v9, v9
	v_lshlrev_b32_e32 v9, 16, v5
	v_fmac_f32_e32 v4, v9, v9
	v_and_b32_e32 v5, 0xffff0000, v5
	v_fmac_f32_e32 v4, v5, v5
	v_lshlrev_b32_e32 v5, 16, v6
	v_fmac_f32_e32 v4, v5, v5
	v_and_b32_e32 v5, 0xffff0000, v6
	v_fmac_f32_e32 v4, v5, v5
	v_lshlrev_b32_e32 v5, 16, v7
	v_fmac_f32_e32 v4, v5, v5
	v_and_b32_e32 v5, 0xffff0000, v7
	v_fmac_f32_e32 v4, v5, v5
	v_lshlrev_b32_e32 v5, 16, v0
	v_and_b32_e32 v0, 0xffff0000, v0
	v_mul_f32_e32 v0, v0, v0
	v_fmac_f32_e32 v0, v5, v5
	v_lshlrev_b32_e32 v5, 16, v1
	v_fmac_f32_e32 v0, v5, v5
	v_and_b32_e32 v1, 0xffff0000, v1
	v_fmac_f32_e32 v0, v1, v1
	v_lshlrev_b32_e32 v1, 16, v2
	v_fmac_f32_e32 v0, v1, v1
	v_and_b32_e32 v1, 0xffff0000, v2
	v_fmac_f32_e32 v0, v1, v1
	v_lshlrev_b32_e32 v1, 16, v3
	v_add_f32_e32 v8, v15, v8
	v_fmac_f32_e32 v0, v1, v1
	v_and_b32_e32 v1, 0xffff0000, v3
	v_add_f32_e32 v4, v8, v4
	v_fmac_f32_e32 v0, v1, v1
	v_add_f32_e32 v18, v4, v0
	s_waitcnt vmcnt(0)
	v_lshlrev_b32_e32 v19, 16, v112
	v_and_b32_e32 v112, 0xffff0000, v112
	v_mul_f32_e32 v112, v112, v112
	v_fmac_f32_e32 v112, v19, v19
	v_lshlrev_b32_e32 v19, 16, v113
	v_fmac_f32_e32 v112, v19, v19
	v_and_b32_e32 v113, 0xffff0000, v113
	v_fmac_f32_e32 v112, v113, v113
	v_lshlrev_b32_e32 v113, 16, v114
	v_fmac_f32_e32 v112, v113, v113
	v_and_b32_e32 v113, 0xffff0000, v114
	v_fmac_f32_e32 v112, v113, v113
	v_lshlrev_b32_e32 v113, 16, v115
	v_fmac_f32_e32 v112, v113, v113
	v_and_b32_e32 v113, 0xffff0000, v115
	v_fmac_f32_e32 v112, v113, v113
	v_lshlrev_b32_e32 v113, 16, v108
	v_and_b32_e32 v108, 0xffff0000, v108
	v_mul_f32_e32 v108, v108, v108
	v_fmac_f32_e32 v108, v113, v113
	v_lshlrev_b32_e32 v113, 16, v109
	v_fmac_f32_e32 v108, v113, v113
	v_and_b32_e32 v109, 0xffff0000, v109
	v_fmac_f32_e32 v108, v109, v109
	v_lshlrev_b32_e32 v109, 16, v110
	v_fmac_f32_e32 v108, v109, v109
	v_and_b32_e32 v109, 0xffff0000, v110
	v_fmac_f32_e32 v108, v109, v109
	v_lshlrev_b32_e32 v109, 16, v111
	v_fmac_f32_e32 v108, v109, v109
	v_and_b32_e32 v109, 0xffff0000, v111
	v_fmac_f32_e32 v108, v109, v109
	v_lshlrev_b32_e32 v109, 16, v104
	v_and_b32_e32 v104, 0xffff0000, v104
	v_mul_f32_e32 v104, v104, v104
	v_fmac_f32_e32 v104, v109, v109
	v_lshlrev_b32_e32 v109, 16, v105
	v_fmac_f32_e32 v104, v109, v109
	v_and_b32_e32 v105, 0xffff0000, v105
	v_fmac_f32_e32 v104, v105, v105
	v_lshlrev_b32_e32 v105, 16, v106
	v_fmac_f32_e32 v104, v105, v105
	v_and_b32_e32 v105, 0xffff0000, v106
	v_fmac_f32_e32 v104, v105, v105
	v_lshlrev_b32_e32 v105, 16, v107
	v_fmac_f32_e32 v104, v105, v105
	v_and_b32_e32 v105, 0xffff0000, v107
	v_fmac_f32_e32 v104, v105, v105
	v_lshlrev_b32_e32 v105, 16, v100
	v_and_b32_e32 v100, 0xffff0000, v100
	v_mul_f32_e32 v100, v100, v100
	v_fmac_f32_e32 v100, v105, v105
	v_lshlrev_b32_e32 v105, 16, v101
	v_fmac_f32_e32 v100, v105, v105
	v_and_b32_e32 v101, 0xffff0000, v101
	v_fmac_f32_e32 v100, v101, v101
	v_lshlrev_b32_e32 v101, 16, v102
	v_fmac_f32_e32 v100, v101, v101
	v_and_b32_e32 v101, 0xffff0000, v102
	v_add_f32_e32 v112, v18, v112
	v_fmac_f32_e32 v100, v101, v101
	v_lshlrev_b32_e32 v101, 16, v103
	v_add_f32_e32 v108, v112, v108
	v_fmac_f32_e32 v100, v101, v101
	v_and_b32_e32 v101, 0xffff0000, v103
	v_add_f32_e32 v104, v108, v104
	v_fmac_f32_e32 v100, v101, v101
	v_lshlrev_b32_e32 v1, 2, v58
	v_add_f32_e32 v0, v104, v100
	v_bitop3_b32 v1, v1, 4, v252 bitop3:0x6c
	ds_bpermute_b32 v1, v1, v0
	s_and_b64 exec, exec, vcc
	s_cbranch_execz .LBB0_759
	s_waitcnt lgkmcnt(0)
	v_add_f32_e32 v0, v0, v1
	v_fmamk_f32 v0, v0, 0x3c000000, v196
	s_mov_b32 s16, 0x800000
	v_mul_f32_e32 v1, 0x4b800000, v0
	v_cmp_gt_f32_e32 vcc, s16, v0
	s_nop 1
	v_cndmask_b32_e32 v0, v0, v1, vcc
	v_rsq_f32_e32 v0, v0
	s_nop 0
	v_mul_f32_e32 v1, 0x45800000, v0
	v_cndmask_b32_e32 v0, v0, v1, vcc
	v_mov_b32_e32 v1, 0x1e000
	v_lshl_add_u32 v1, v16, 2, v1
	ds_write_b32 v1, v0

; #define OPQ int tid = tid0; asm volatile("" : "+v"(tid));
; DEV void qproj_item(const Params& p, int l, int tt, int tf, char* smem, int tid) {
;   const int t0 = tt * 192, f0 = tf * 128;
;   f32x4 acc[2][6];
;   zero_acc<2, 6>(acc);
;   float* rs = (float*)(smem + 122880);
;   __syncthreads();
;   row_scales(p.z + (long)t0 * NINP, C_CQ, 256, rs, tid);
;   gemm_mainloop<2, 6>(p.WuqT + ((long)l * 768 + f0) * 256, 256, p.z + (long)t0 * NINP + C_CQ, NINP, 256, smem, tid, acc);
; __global__ void __launch_bounds__(512) mega(Params p, int coop) {
;     ...
;         for (int j = xr; j < 72 + 96 + 9; j += xper) {
;           OPQ
;           if (j < 72) { if (!(last && (j % 12) == 0)) qproj_item(p, l, xx * 12 + j % 12, j / 12, smem, tid); }
.LBB0_767:
	s_mul_i32 s6, s15, 43
	s_lshr_b32 s16, s6, 8
	s_mul_i32 s6, s16, 6
	s_sub_i32 s10, s15, s6
	s_cmp_eq_u32 s16, 0
	v_readlane_b32 s8, v255, 42
	s_cselect_b64 s[6:7], -1, 0
	v_readlane_b32 s9, v255, 43
	s_and_b64 s[6:7], s[8:9], s[6:7]
	s_and_b64 vcc, exec, s[6:7]
	s_cbranch_vccnz .LBB0_749
	v_readlane_b32 s6, v255, 10
	s_add_i32 s16, s16, s6
	s_mul_i32 s17, s16, 0xc0
	s_movk_i32 s8, 0x180
	s_mul_i32 s6, s16, 0x330000
	s_mul_hi_i32 s7, s17, 0x4400
	v_cmp_gt_i32_e32 vcc, s8, v58
	s_waitcnt vmcnt(0)
	s_barrier
	s_and_saveexec_b64 s[8:9], vcc
	s_cbranch_execz .LBB0_773
	v_ashrrev_i32_e32 v2, 1, v58
	v_mov_b64_e32 v[0:1], s[6:7]
	v_mad_i64_i32 v[0:1], s[18:19], v2, s33, v[0:1]
	v_and_b32_e32 v3, 1, v58
	v_lshlrev_b32_e32 v156, 8, v3
	v_readlane_b32 s18, v254, 37
	v_lshl_add_u64 v[0:1], v[0:1], 0, v[156:157]
	v_readlane_b32 s19, v254, 38
	v_mov_b32_e32 v4, 0
	s_mov_b32 s11, -8
	v_lshl_add_u64 v[0:1], s[18:19], 0, v[0:1]
